# up-GEMM K-loop load segments: LDS-DMA issues interleaved between the fragment ds_reads (were a read burst then a DMA burst)
# speedup vs baseline: 1.0284x; 1.0284x over previous
; #define PG8_STAGE(bufoff, gbase, voff) do { _Pragma("unroll") for (int _i = 0; _i < 2; ++_i) \
;         __builtin_amdgcn_global_load_lds((const unsigned*)((const char*)(gbase) + (voff)[_i]), (PG8_LAS unsigned*)(lds + (bufoff) + ldsw + _i * 8192), 16, 0, 0); } while (0)
; #define PG8_LDA(dst, b, h) do { _Pragma("unroll") for (int m = 0; m < 4; ++m) _Pragma("unroll") for (int k = 0; k < 2; ++k) dst[m][k] = *(const PG8_LAS bf16x8*)(lds + PG8_SA(b, h) + aoff + m * 2048 + k * 1024); } while (0)
; #define PG8_LDB(dst, b, h) do { _Pragma("unroll") for (int n = 0; n < 2; ++n) _Pragma("unroll") for (int k = 0; k < 2; ++k) dst[n][k] = *(const PG8_LAS bf16x8*)(lds + PG8_SB(b, h) + boff + n * 2048 + k * 1024); } while (0)
; #define PG8_MMA(ai, bj, At, Bt) do { __builtin_amdgcn_s_setprio(1); _Pragma("unroll") for (int m = 0; m < 4; ++m) _Pragma("unroll") for (int n = 0; n < 2; ++n) _Pragma("unroll") for (int k = 0; k < 2; ++k) \
;         acc[ai][bj][m][n] = __builtin_amdgcn_mfma_f32_16x16x32_bf16(Bt[n][k], At[m][k], acc[ai][bj][m][n], 0, 0, 0); __builtin_amdgcn_s_setprio(0); } while (0)
; #define PG8_WAIT_V(n) asm volatile("s_waitcnt vmcnt(" #n ")" ::: "memory")
; #define PG8_WAIT_L(n) asm volatile("s_waitcnt lgkmcnt(" #n ")" ::: "memory")
; #define PG8_BAR __builtin_amdgcn_s_barrier()
; #define PG8_SCHED __builtin_amdgcn_sched_barrier(0)
; template <class Epi, class Sched, bool ALIGN_EPI = false, bool SP2 = false>
; __device__ __forceinline__ void gemm_phase(PG8_LAS unsigned char* lds, const Gemm g, const Sched& S, const Epi& E) {
;     ...
;             PG8_LDB(B0, 0, 0); PG8_LDB(B1, 0, 1); PG8_SCHED; PG8_LDA(At, 0, 0); PG8_STAGE(PG8_SA(1, 1), a1 + hstep, voffA);
;             PG8_WAIT_V(8); PG8_WAIT_L(0); PG8_BAR; PG8_MMA(0, 0, At, B0); PG8_MMA(0, 1, At, B1); PG8_BAR; PG8_SCHED;
;             PG8_LDA(At, 0, 1); PG8_STAGE(PG8_SB(0, 0), b2, voffB); PG8_STAGE(PG8_SB(0, 1), b2 + hstep, voffB); PG8_STAGE(PG8_SA(0, 0), a2, voffA);
;             PG8_WAIT_V(8); PG8_WAIT_L(0); PG8_BAR; PG8_MMA(1, 0, At, B0); PG8_MMA(1, 1, At, B1); PG8_BAR; PG8_SCHED;
.LBB0_55:
	s_add_u32 s28, s42, 0xfff80080
	s_addc_u32 s29, s43, -1
	s_add_i32 s72, 0, 0x10000
	s_cmp_eq_u32 s71, 28
	s_cselect_b32 s53, s27, s29
	s_cselect_b32 s52, s65, s28
	s_cselect_b32 s51, s25, s70
	s_cselect_b32 s50, s66, s67
	s_add_i32 s73, 0, 0x14000
	s_add_i32 m0, s12, 0xc000
	ds_read_b128 v[64:67], v192
	global_load_lds_dwordx4 v152, s[42:43]
	ds_read_b128 v[68:71], v192 offset:1024
	ds_read_b128 v[72:75], v192 offset:2048
	ds_read_b128 v[76:79], v192 offset:3072
	ds_read_b128 v[156:159], v193
	ds_read_b128 v[168:171], v193 offset:1024
	ds_read_b128 v[172:175], v193 offset:2048
	ds_read_b128 v[176:179], v193 offset:3072
	s_add_i32 m0, s12, 0xe000
	ds_read_b128 v[180:183], v165
	global_load_lds_dwordx4 v154, s[42:43]
	ds_read_b128 v[184:187], v165 offset:1024
	ds_read_b128 v[188:191], v165 offset:2048
	ds_read_b128 v[196:199], v165 offset:3072
	ds_read_b128 v[200:203], v165 offset:4096
	ds_read_b128 v[204:207], v165 offset:5120
	ds_read_b128 v[208:211], v165 offset:6144
	ds_read_b128 v[222:225], v165 offset:7168
	s_waitcnt vmcnt(8)
	s_waitcnt lgkmcnt(0)
	s_barrier
	s_setprio 1
	s_waitcnt lgkmcnt(0)
	v_mfma_f32_16x16x32_bf16 v[140:143], v[64:67], v[180:183], v[140:143]
	v_mfma_f32_16x16x32_bf16 v[136:139], v[72:75], v[180:183], v[136:139]
	v_mfma_f32_16x16x32_bf16 v[124:127], v[64:67], v[188:191], v[124:127]
	v_mfma_f32_16x16x32_bf16 v[120:123], v[72:75], v[188:191], v[120:123]
	v_mfma_f32_16x16x32_bf16 v[108:111], v[64:67], v[200:203], v[108:111]
	v_mfma_f32_16x16x32_bf16 v[104:107], v[72:75], v[200:203], v[104:107]
	v_mfma_f32_16x16x32_bf16 v[92:95], v[64:67], v[208:211], v[92:95]
	v_mfma_f32_16x16x32_bf16 v[88:91], v[72:75], v[208:211], v[88:91]
	v_mfma_f32_16x16x32_bf16 v[140:143], v[68:71], v[184:187], v[140:143]
	v_mfma_f32_16x16x32_bf16 v[136:139], v[76:79], v[184:187], v[136:139]
	v_mfma_f32_16x16x32_bf16 v[124:127], v[68:71], v[196:199], v[124:127]
	v_mfma_f32_16x16x32_bf16 v[120:123], v[76:79], v[196:199], v[120:123]
	v_mfma_f32_16x16x32_bf16 v[108:111], v[68:71], v[204:207], v[108:111]
	v_mfma_f32_16x16x32_bf16 v[104:107], v[76:79], v[204:207], v[104:107]
	v_mfma_f32_16x16x32_bf16 v[92:95], v[68:71], v[222:225], v[92:95]
	v_mfma_f32_16x16x32_bf16 v[88:91], v[76:79], v[222:225], v[88:91]
	s_setprio 0
	s_setprio 1
	v_mfma_f32_16x16x32_bf16 v[132:135], v[156:159], v[180:183], v[132:135]
	v_mfma_f32_16x16x32_bf16 v[128:131], v[172:175], v[180:183], v[128:131]
	v_mfma_f32_16x16x32_bf16 v[116:119], v[156:159], v[188:191], v[116:119]
	v_mfma_f32_16x16x32_bf16 v[112:115], v[172:175], v[188:191], v[112:115]
	v_mfma_f32_16x16x32_bf16 v[100:103], v[156:159], v[200:203], v[100:103]
	v_mfma_f32_16x16x32_bf16 v[96:99], v[172:175], v[200:203], v[96:99]
	v_mfma_f32_16x16x32_bf16 v[84:87], v[156:159], v[208:211], v[84:87]
	v_mfma_f32_16x16x32_bf16 v[80:83], v[172:175], v[208:211], v[80:83]
	v_mfma_f32_16x16x32_bf16 v[132:135], v[168:171], v[184:187], v[132:135]
	v_mfma_f32_16x16x32_bf16 v[128:131], v[176:179], v[184:187], v[128:131]
	v_mfma_f32_16x16x32_bf16 v[116:119], v[168:171], v[196:199], v[116:119]
	v_mfma_f32_16x16x32_bf16 v[112:115], v[176:179], v[196:199], v[112:115]
	v_mfma_f32_16x16x32_bf16 v[100:103], v[168:171], v[204:207], v[100:103]
	v_mfma_f32_16x16x32_bf16 v[96:99], v[176:179], v[204:207], v[96:99]
	v_mfma_f32_16x16x32_bf16 v[84:87], v[168:171], v[222:225], v[84:87]
	v_mfma_f32_16x16x32_bf16 v[80:83], v[176:179], v[222:225], v[80:83]
	s_setprio 0
	s_barrier
	s_add_i32 s28, s72, s8
	s_mov_b32 m0, s28
	ds_read_b128 v[180:183], v165 offset:16384
	global_load_lds_dwordx4 v194, s[50:51]
	s_add_i32 m0, s28, 0x2000
	s_add_u32 s28, s50, 0x80000
	s_addc_u32 s29, s51, 0
	s_add_i32 s72, s73, s8
	ds_read_b128 v[184:187], v165 offset:17408
	global_load_lds_dwordx4 v144, s[50:51]
	s_mov_b32 m0, s72
	ds_read_b128 v[188:191], v165 offset:18432
	global_load_lds_dwordx4 v194, s[28:29]
	s_add_i32 m0, s72, 0x2000
	ds_read_b128 v[196:199], v165 offset:19456
	global_load_lds_dwordx4 v144, s[28:29]
	s_mov_b32 m0, s12
	ds_read_b128 v[200:203], v165 offset:20480
	global_load_lds_dwordx4 v148, s[52:53]
	s_mov_b32 m0, s20
	ds_read_b128 v[204:207], v165 offset:21504
	global_load_lds_dwordx4 v146, s[52:53]
	ds_read_b128 v[208:211], v165 offset:22528
	ds_read_b128 v[222:225], v165 offset:23552
	s_waitcnt vmcnt(8)
	s_waitcnt lgkmcnt(0)
	s_barrier
	s_setprio 1
	s_waitcnt lgkmcnt(0)
	v_mfma_f32_16x16x32_bf16 v[60:63], v[64:67], v[180:183], v[60:63]
	v_mfma_f32_16x16x32_bf16 v[56:59], v[72:75], v[180:183], v[56:59]
	v_mfma_f32_16x16x32_bf16 v[44:47], v[64:67], v[188:191], v[44:47]
	v_mfma_f32_16x16x32_bf16 v[40:43], v[72:75], v[188:191], v[40:43]
	v_mfma_f32_16x16x32_bf16 v[28:31], v[64:67], v[200:203], v[28:31]
	v_mfma_f32_16x16x32_bf16 v[24:27], v[72:75], v[200:203], v[24:27]
	v_mfma_f32_16x16x32_bf16 v[12:15], v[64:67], v[208:211], v[12:15]
	v_mfma_f32_16x16x32_bf16 v[8:11], v[72:75], v[208:211], v[8:11]
	v_mfma_f32_16x16x32_bf16 v[60:63], v[68:71], v[184:187], v[60:63]
	v_mfma_f32_16x16x32_bf16 v[56:59], v[76:79], v[184:187], v[56:59]
	v_mfma_f32_16x16x32_bf16 v[44:47], v[68:71], v[196:199], v[44:47]
	v_mfma_f32_16x16x32_bf16 v[40:43], v[76:79], v[196:199], v[40:43]
	v_mfma_f32_16x16x32_bf16 v[28:31], v[68:71], v[204:207], v[28:31]
	v_mfma_f32_16x16x32_bf16 v[24:27], v[76:79], v[204:207], v[24:27]
	v_mfma_f32_16x16x32_bf16 v[12:15], v[68:71], v[222:225], v[12:15]
	v_mfma_f32_16x16x32_bf16 v[8:11], v[76:79], v[222:225], v[8:11]
	s_setprio 0
	s_setprio 1
	v_mfma_f32_16x16x32_bf16 v[52:55], v[156:159], v[180:183], v[52:55]
	v_mfma_f32_16x16x32_bf16 v[48:51], v[172:175], v[180:183], v[48:51]
	v_mfma_f32_16x16x32_bf16 v[36:39], v[156:159], v[188:191], v[36:39]
	v_mfma_f32_16x16x32_bf16 v[32:35], v[172:175], v[188:191], v[32:35]
	v_mfma_f32_16x16x32_bf16 v[20:23], v[156:159], v[200:203], v[20:23]
	v_mfma_f32_16x16x32_bf16 v[16:19], v[172:175], v[200:203], v[16:19]
	v_mfma_f32_16x16x32_bf16 v[4:7], v[156:159], v[208:211], v[4:7]
	v_mfma_f32_16x16x32_bf16 v[0:3], v[172:175], v[208:211], v[0:3]
	v_mfma_f32_16x16x32_bf16 v[52:55], v[168:171], v[184:187], v[52:55]
	v_mfma_f32_16x16x32_bf16 v[48:51], v[176:179], v[184:187], v[48:51]
	v_mfma_f32_16x16x32_bf16 v[36:39], v[168:171], v[196:199], v[36:39]
	v_mfma_f32_16x16x32_bf16 v[32:35], v[176:179], v[196:199], v[32:35]
	v_mfma_f32_16x16x32_bf16 v[20:23], v[168:171], v[204:207], v[20:23]
	v_mfma_f32_16x16x32_bf16 v[16:19], v[176:179], v[204:207], v[16:19]
	v_mfma_f32_16x16x32_bf16 v[4:7], v[168:171], v[222:225], v[4:7]
	v_mfma_f32_16x16x32_bf16 v[0:3], v[176:179], v[222:225], v[0:3]
	s_setprio 0
	s_barrier
; #define PG8_STAGE(bufoff, gbase, voff) do { _Pragma("unroll") for (int _i = 0; _i < 2; ++_i) \
;         __builtin_amdgcn_global_load_lds((const unsigned*)((const char*)(gbase) + (voff)[_i]), (PG8_LAS unsigned*)(lds + (bufoff) + ldsw + _i * 8192), 16, 0, 0); } while (0)
; #define PG8_LDA(dst, b, h) do { _Pragma("unroll") for (int m = 0; m < 4; ++m) _Pragma("unroll") for (int k = 0; k < 2; ++k) dst[m][k] = *(const PG8_LAS bf16x8*)(lds + PG8_SA(b, h) + aoff + m * 2048 + k * 1024); } while (0)
; #define PG8_LDB(dst, b, h) do { _Pragma("unroll") for (int n = 0; n < 2; ++n) _Pragma("unroll") for (int k = 0; k < 2; ++k) dst[n][k] = *(const PG8_LAS bf16x8*)(lds + PG8_SB(b, h) + boff + n * 2048 + k * 1024); } while (0)
; #define PG8_MMA(ai, bj, At, Bt) do { __builtin_amdgcn_s_setprio(1); _Pragma("unroll") for (int m = 0; m < 4; ++m) _Pragma("unroll") for (int n = 0; n < 2; ++n) _Pragma("unroll") for (int k = 0; k < 2; ++k) \
;         acc[ai][bj][m][n] = __builtin_amdgcn_mfma_f32_16x16x32_bf16(Bt[n][k], At[m][k], acc[ai][bj][m][n], 0, 0, 0); __builtin_amdgcn_s_setprio(0); } while (0)
; #define PG8_WAIT_V(n) asm volatile("s_waitcnt vmcnt(" #n ")" ::: "memory")
; #define PG8_WAIT_L(n) asm volatile("s_waitcnt lgkmcnt(" #n ")" ::: "memory")
; #define PG8_BAR __builtin_amdgcn_s_barrier()
; #define PG8_SCHED __builtin_amdgcn_sched_barrier(0)
; template <class Epi, class Sched, bool ALIGN_EPI = false, bool SP2 = false>
; __device__ __forceinline__ void gemm_phase(PG8_LAS unsigned char* lds, const Gemm g, const Sched& S, const Epi& E) {
;     ...
;             PG8_LDB(B0, 1, 0); PG8_LDB(B1, 1, 1); PG8_SCHED; PG8_LDA(At, 1, 0); PG8_STAGE(PG8_SA(0, 1), a2 + hstep, voffA);
;             PG8_WAIT_V(8); PG8_WAIT_L(0); PG8_BAR; PG8_MMA(0, 0, At, B0); PG8_MMA(0, 1, At, B1); PG8_BAR; PG8_SCHED;
;             PG8_LDA(At, 1, 1); PG8_STAGE(PG8_SB(1, 0), b3, voffB); PG8_STAGE(PG8_SB(1, 1), b3 + hstep, voffB); PG8_STAGE(PG8_SA(1, 0), a3, voffA);
;             PG8_WAIT_V(8); PG8_WAIT_L(0); PG8_BAR; PG8_MMA(1, 0, At, B0); PG8_MMA(1, 1, At, B1); PG8_BAR; PG8_SCHED;
	s_add_i32 s72, 0, 0x18000
	s_add_i32 s73, 0, 0x1c000
	s_add_u32 s28, s52, 0x80000
	s_addc_u32 s29, s53, 0
	s_mov_b32 m0, s21
	ds_read_b128 v[64:67], v212
	global_load_lds_dwordx4 v148, s[28:29]
	ds_read_b128 v[68:71], v212 offset:1024
	ds_read_b128 v[72:75], v212 offset:2048
	ds_read_b128 v[76:79], v212 offset:3072
	ds_read_b128 v[156:159], v213
	ds_read_b128 v[168:171], v213 offset:1024
	ds_read_b128 v[172:175], v213 offset:2048
	ds_read_b128 v[176:179], v213 offset:3072
	s_mov_b32 m0, s48
	ds_read_b128 v[180:183], v165 offset:32768
	global_load_lds_dwordx4 v146, s[28:29]
	ds_read_b128 v[184:187], v165 offset:33792
	ds_read_b128 v[188:191], v165 offset:34816
	ds_read_b128 v[196:199], v165 offset:35840
	ds_read_b128 v[200:203], v165 offset:36864
	ds_read_b128 v[204:207], v165 offset:37888
	ds_read_b128 v[208:211], v165 offset:38912
	ds_read_b128 v[222:225], v165 offset:39936
	s_waitcnt vmcnt(8)
	s_waitcnt lgkmcnt(0)
	s_barrier
	s_setprio 1
	s_waitcnt lgkmcnt(0)
	v_mfma_f32_16x16x32_bf16 v[140:143], v[64:67], v[180:183], v[140:143]
	v_mfma_f32_16x16x32_bf16 v[136:139], v[72:75], v[180:183], v[136:139]
	v_mfma_f32_16x16x32_bf16 v[124:127], v[64:67], v[188:191], v[124:127]
	v_mfma_f32_16x16x32_bf16 v[120:123], v[72:75], v[188:191], v[120:123]
	v_mfma_f32_16x16x32_bf16 v[108:111], v[64:67], v[200:203], v[108:111]
	v_mfma_f32_16x16x32_bf16 v[104:107], v[72:75], v[200:203], v[104:107]
	v_mfma_f32_16x16x32_bf16 v[92:95], v[64:67], v[208:211], v[92:95]
	v_mfma_f32_16x16x32_bf16 v[88:91], v[72:75], v[208:211], v[88:91]
	v_mfma_f32_16x16x32_bf16 v[140:143], v[68:71], v[184:187], v[140:143]
	v_mfma_f32_16x16x32_bf16 v[136:139], v[76:79], v[184:187], v[136:139]
	v_mfma_f32_16x16x32_bf16 v[124:127], v[68:71], v[196:199], v[124:127]
	v_mfma_f32_16x16x32_bf16 v[120:123], v[76:79], v[196:199], v[120:123]
	v_mfma_f32_16x16x32_bf16 v[108:111], v[68:71], v[204:207], v[108:111]
	v_mfma_f32_16x16x32_bf16 v[104:107], v[76:79], v[204:207], v[104:107]
	v_mfma_f32_16x16x32_bf16 v[92:95], v[68:71], v[222:225], v[92:95]
	v_mfma_f32_16x16x32_bf16 v[88:91], v[76:79], v[222:225], v[88:91]
	s_setprio 0
	s_setprio 1
	v_mfma_f32_16x16x32_bf16 v[132:135], v[156:159], v[180:183], v[132:135]
	v_mfma_f32_16x16x32_bf16 v[128:131], v[172:175], v[180:183], v[128:131]
	v_mfma_f32_16x16x32_bf16 v[116:119], v[156:159], v[188:191], v[116:119]
	v_mfma_f32_16x16x32_bf16 v[112:115], v[172:175], v[188:191], v[112:115]
	v_mfma_f32_16x16x32_bf16 v[100:103], v[156:159], v[200:203], v[100:103]
	v_mfma_f32_16x16x32_bf16 v[96:99], v[172:175], v[200:203], v[96:99]
	v_mfma_f32_16x16x32_bf16 v[84:87], v[156:159], v[208:211], v[84:87]
	v_mfma_f32_16x16x32_bf16 v[80:83], v[172:175], v[208:211], v[80:83]
	v_mfma_f32_16x16x32_bf16 v[132:135], v[168:171], v[184:187], v[132:135]
	v_mfma_f32_16x16x32_bf16 v[128:131], v[176:179], v[184:187], v[128:131]
	v_mfma_f32_16x16x32_bf16 v[116:119], v[168:171], v[196:199], v[116:119]
	v_mfma_f32_16x16x32_bf16 v[112:115], v[176:179], v[196:199], v[112:115]
	v_mfma_f32_16x16x32_bf16 v[100:103], v[168:171], v[204:207], v[100:103]
	v_mfma_f32_16x16x32_bf16 v[96:99], v[176:179], v[204:207], v[96:99]
	v_mfma_f32_16x16x32_bf16 v[84:87], v[168:171], v[222:225], v[84:87]
	v_mfma_f32_16x16x32_bf16 v[80:83], v[176:179], v[222:225], v[80:83]
	s_setprio 0
	s_barrier
	s_add_i32 s28, s72, s8
	s_add_u32 s98, s50, 0x80
	s_addc_u32 s99, s51, 0
	s_mov_b32 m0, s28
	ds_read_b128 v[180:183], v165 offset:49152
	global_load_lds_dwordx4 v194, s[98:99]
	s_add_i32 m0, s28, 0x2000
	s_add_u32 s28, s50, 0x80080
	s_addc_u32 s29, s51, 0
	s_add_i32 s50, s73, s8
	ds_read_b128 v[184:187], v165 offset:50176
	global_load_lds_dwordx4 v144, s[98:99]
	s_mov_b32 m0, s50
	s_add_u32 s100, s52, 0x80
	s_addc_u32 s101, s53, 0
	ds_read_b128 v[188:191], v165 offset:51200
	global_load_lds_dwordx4 v194, s[28:29]
	s_add_i32 m0, s50, 0x2000
	ds_read_b128 v[196:199], v165 offset:52224
	global_load_lds_dwordx4 v144, s[28:29]
	s_mov_b32 m0, s55
	ds_read_b128 v[200:203], v165 offset:53248
	global_load_lds_dwordx4 v148, s[100:101]
	s_mov_b32 m0, s60
	ds_read_b128 v[204:207], v165 offset:54272
	global_load_lds_dwordx4 v146, s[100:101]
	ds_read_b128 v[208:211], v165 offset:55296
	ds_read_b128 v[222:225], v165 offset:56320
	s_waitcnt vmcnt(8)
	s_waitcnt lgkmcnt(0)
	s_barrier
	s_setprio 1
	s_waitcnt lgkmcnt(0)
	v_mfma_f32_16x16x32_bf16 v[60:63], v[64:67], v[180:183], v[60:63]
	v_mfma_f32_16x16x32_bf16 v[56:59], v[72:75], v[180:183], v[56:59]
	v_mfma_f32_16x16x32_bf16 v[44:47], v[64:67], v[188:191], v[44:47]
	v_mfma_f32_16x16x32_bf16 v[40:43], v[72:75], v[188:191], v[40:43]
	v_mfma_f32_16x16x32_bf16 v[28:31], v[64:67], v[200:203], v[28:31]
	v_mfma_f32_16x16x32_bf16 v[24:27], v[72:75], v[200:203], v[24:27]
	v_mfma_f32_16x16x32_bf16 v[12:15], v[64:67], v[208:211], v[12:15]
	v_mfma_f32_16x16x32_bf16 v[8:11], v[72:75], v[208:211], v[8:11]
	v_mfma_f32_16x16x32_bf16 v[60:63], v[68:71], v[184:187], v[60:63]
	v_mfma_f32_16x16x32_bf16 v[56:59], v[76:79], v[184:187], v[56:59]
	v_mfma_f32_16x16x32_bf16 v[44:47], v[68:71], v[196:199], v[44:47]
	v_mfma_f32_16x16x32_bf16 v[40:43], v[76:79], v[196:199], v[40:43]
	v_mfma_f32_16x16x32_bf16 v[28:31], v[68:71], v[204:207], v[28:31]
	v_mfma_f32_16x16x32_bf16 v[24:27], v[76:79], v[204:207], v[24:27]
	v_mfma_f32_16x16x32_bf16 v[12:15], v[68:71], v[222:225], v[12:15]
	v_mfma_f32_16x16x32_bf16 v[8:11], v[76:79], v[222:225], v[8:11]
	s_setprio 0
	s_setprio 1
	v_mfma_f32_16x16x32_bf16 v[52:55], v[156:159], v[180:183], v[52:55]
	v_mfma_f32_16x16x32_bf16 v[48:51], v[172:175], v[180:183], v[48:51]
	v_mfma_f32_16x16x32_bf16 v[36:39], v[156:159], v[188:191], v[36:39]
	v_mfma_f32_16x16x32_bf16 v[32:35], v[172:175], v[188:191], v[32:35]
	v_mfma_f32_16x16x32_bf16 v[20:23], v[156:159], v[200:203], v[20:23]
	v_mfma_f32_16x16x32_bf16 v[16:19], v[172:175], v[200:203], v[16:19]
	v_mfma_f32_16x16x32_bf16 v[4:7], v[156:159], v[208:211], v[4:7]
	v_mfma_f32_16x16x32_bf16 v[0:3], v[172:175], v[208:211], v[0:3]
	v_mfma_f32_16x16x32_bf16 v[52:55], v[168:171], v[184:187], v[52:55]
	v_mfma_f32_16x16x32_bf16 v[48:51], v[176:179], v[184:187], v[48:51]
	v_mfma_f32_16x16x32_bf16 v[36:39], v[168:171], v[196:199], v[36:39]
	v_mfma_f32_16x16x32_bf16 v[32:35], v[176:179], v[196:199], v[32:35]
	v_mfma_f32_16x16x32_bf16 v[20:23], v[168:171], v[204:207], v[20:23]
	v_mfma_f32_16x16x32_bf16 v[16:19], v[176:179], v[204:207], v[16:19]
	v_mfma_f32_16x16x32_bf16 v[4:7], v[168:171], v[222:225], v[4:7]
	v_mfma_f32_16x16x32_bf16 v[0:3], v[176:179], v[222:225], v[0:3]
	s_setprio 0
	s_barrier
	s_add_i32 s71, s71, 2
	s_add_u32 s42, s42, 0x100
	s_addc_u32 s43, s43, 0
	s_add_u32 s67, s67, 0x100
	s_addc_u32 s70, s70, 0
	s_cmp_gt_u32 s71, 29
	s_cbranch_scc0 .LBB0_55
	s_and_b64 vcc, exec, s[22:23]
	s_cbranch_vccz .LBB0_58
	s_barrier
